# attn1 unit prologue de-serialised: parallel j0 search (1 round-trip instead of 7), Q loads hoisted above search, tile0+tile1 loads issued together
# speedup vs baseline: 1.0038x; 1.0036x over previous
;     ...
;         if (MODE == 1) {
;             const unsigned* bnd = (const unsigned*)(ws + WS_BND) + (b * 8 + h) * 2;
;             const float Bnd = sqrtf(__uint_as_float(bnd[0]) * __uint_as_float(bnd[1])) * 1.02f + 0.5f;
;             const float thr = -(2.0f * Bnd + 30.0f);
;             const float* cc = c2 + (size_t)(b * 8 + h) * SEQ;
;             const float cq0 = cc[q0];
;             int lo = 0, hi = q0 >> 6;
;             while (lo < hi) { const int mid = (lo + hi) >> 1; if (cq0 - cc[64 * mid + 63] >= thr) hi = mid; else lo = mid + 1; }
;             j0 = lo;
;         }
;     ...
;         bf16x8 qf[4];
; #pragma unroll
;         for (int ks = 0; ks < 4; ++ks) qf[ks] = *(const bf16x8*)(P + (size_t)(b * SEQ + myq) * PITCH + qcol + 16 * ks + 8 * hh);
.LBB0_1326:
	s_andn2_b64 vcc, exec, s[6:7]
	s_cbranch_vccnz .LBB0_1319
	s_ashr_i32 s19, s18, 31
	s_lshl_b32 s8, s49, 8
	s_lshl_b64 s[0:1], s[18:19], 15
	s_add_u32 s20, s30, s0
	s_addc_u32 s21, s31, s1
	s_lshr_b32 s0, s19, 29
	s_add_i32 s1, s18, s0
	s_ashr_i32 s0, s1, 3
	s_and_b32 s1, s1, -8
	s_sub_i32 s1, s18, s1
	v_add_u32_e32 v188, s8, v155
	s_lshl_b32 s9, s0, 13
	v_or_b32_e32 v189, v188, v185
	v_or_b32_e32 v2, s9, v191
	v_mov_b64_e32 v[4:5], s[10:11]
	s_lshl_b32 s22, s1, 6
	s_lshl_b32 s0, s0, 9
	v_mad_i64_i32 v[6:7], s[6:7], v2, s40, v[4:5]
	s_ashr_i32 s23, s22, 31
	s_add_i32 s0, s0, s22
	v_add_u32_e32 v160, s9, v189
	s_lshl_b64 s[6:7], s[22:23], 1
	v_add_u32_e32 v8, s0, v191
	v_mad_i64_i32 v[4:5], s[0:1], v160, s40, v[4:5]
	v_lshl_add_u64 v[4:5], v[4:5], 0, s[6:7]
	s_waitcnt vmcnt(8)
	v_mov_b32_e32 v157, v3
	v_lshl_add_u64 v[6:7], v[6:7], 0, s[6:7]
	v_lshl_add_u64 v[4:5], v[4:5], 0, v[156:157]
	v_mov_b32_e32 v151, v3
	global_load_dwordx4 v[126:129], v[4:5], off offset:3072
	global_load_dwordx4 v[130:133], v[4:5], off offset:3104
	global_load_dwordx4 v[134:137], v[4:5], off offset:3136
	global_load_dwordx4 v[138:141], v[4:5], off offset:3168
	v_lshl_add_u64 v[4:5], v[6:7], 0, v[150:151]
	v_ashrrev_i32_e32 v9, 31, v8
	v_lshl_add_u64 v[162:163], v[4:5], 0, s[14:15]
	v_lshlrev_b64 v[8:9], 14, v[8:9]
	v_lshl_add_u64 v[164:165], v[152:153], 0, v[8:9]
	s_cmp_lt_i32 s49, 1
	s_cbranch_scc1 .LBB0_1330
	s_lshl_b32 s0, s18, 1
	s_ashr_i32 s1, s0, 31
	s_lshl_b64 s[0:1], s[0:1], 2
	s_add_u32 s0, s36, s0
	s_addc_u32 s1, s37, s1
	global_load_dwordx2 v[4:5], v3, s[0:1]
	s_ashr_i32 s9, s8, 31
	s_lshl_b64 s[0:1], s[8:9], 2
	s_add_u32 s0, s20, s0
	s_addc_u32 s1, s21, s1
	global_load_dword v2, v3, s[0:1]
	v_mbcnt_lo_u32_b32 v10, -1, 0
	v_mbcnt_hi_u32_b32 v10, -1, v10
	v_lshlrev_b32_e32 v11, 8, v10
	v_add_u32_e32 v12, 0x4000, v11
	global_load_dword v13, v11, s[20:21] offset:252
	global_load_dword v14, v12, s[20:21] offset:252
	v_add_u32_e32 v11, 64, v10
	s_lshl_b32 s0, s49, 2
	s_waitcnt vmcnt(3)
	v_mul_f32_e32 v4, v4, v5
	v_mul_f32_e32 v5, 0x4f800000, v4
	v_cmp_gt_f32_e32 vcc, s38, v4
	s_nop 1
	v_cndmask_b32_e32 v4, v4, v5, vcc
	v_sqrt_f32_e32 v5, v4
	s_nop 0
	v_add_u32_e32 v6, -1, v5
	v_add_u32_e32 v7, 1, v5
	v_fma_f32 v8, -v6, v5, v4
	v_fma_f32 v9, -v7, v5, v4
	v_cmp_ge_f32_e64 s[6:7], 0, v8
	s_nop 1
	v_cndmask_b32_e64 v5, v5, v6, s[6:7]
	v_cmp_lt_f32_e64 s[6:7], 0, v9
	s_nop 1
	v_cndmask_b32_e64 v5, v5, v7, s[6:7]
	v_mul_f32_e32 v6, 0x37800000, v5
	v_cndmask_b32_e32 v5, v5, v6, vcc
	v_cmp_class_f32_e32 vcc, v4, v183
	s_nop 1
	v_cndmask_b32_e32 v4, v5, v4, vcc
	v_fma_f32 v4, v4, s39, 0.5
	v_fmaak_f32 v4, 2.0, v4, 0x41f00000
	s_waitcnt vmcnt(0)
	v_cmp_gt_i32_e64 s[26:27], s0, v10
	v_sub_f32_e32 v13, v2, v13
	v_sub_f32_e32 v14, v2, v14
	v_cmp_ge_f32_e64 s[6:7], v13, -v4
	v_cmp_gt_i32_e32 vcc, s0, v11
	s_and_b64 s[6:7], s[6:7], s[26:27]
	v_cmp_ge_f32_e64 s[26:27], v14, -v4
	s_ff1_i32_b64 s24, s[6:7]
	s_and_b64 s[26:27], s[26:27], vcc
	s_ff1_i32_b64 s1, s[26:27]
	s_add_i32 s1, s1, 64
	s_cmp_lg_u64 s[26:27], 0
	s_cselect_b32 s1, s1, s0
	s_cmp_lg_u64 s[6:7], 0
	s_cselect_b32 s24, s24, s1
	s_branch .LBB0_1331

;     ...
;         auto gload = [&](u32x4 (&rg)[NJ], float& ckr, int t) {
; #pragma unroll
;             for (int j = 0; j < NJ; ++j) rg[j] = *(const u32x4*)(src[j] + (size_t)t * step[j]);
;             if (MODE == 1 && tid < 64) ckr = ckp[t * 64 + tid];
;         };
;         auto lstore = [&](const u32x4 (&rg)[NJ], const float ckr, int stg) {
;             unsigned char* sb = lds + stg * STG;
; #pragma unroll
;             for (int j = 0; j < NJ; ++j) {
;                 if (j < NKJ) *(u32x4*)(sb + j * 9216 + lrow * 144 + lkc * 16) = rg[j];
;                 else { unsigned char* d = sb + VT_OFF + (lrow + 64 * (j - NKJ)) * 136 + lkc * 16; u32x2 a, c; a.x = rg[j].x; a.y = rg[j].y; c.x = rg[j].z; c.y = rg[j].w; *(u32x2*)d = a; *(u32x2*)(d + 8) = c; }
;             }
;             if (MODE == 1 && tid < 64) *(float*)(sb + CK_OFF + tid * 4) = ckr;
;         };
;     ...
;         gload(rgE, ckrE, j0); lstore(rgE, ckrE, 0);
;         if (ntl > 1) { gload(rgE, ckrE, j0 + 1); lstore(rgE, ckrE, 1); }
;         if (DEEP && ntl > 2) gload(rgO, ckrO, j0 + 2);
;         if (MODE == 2 && ntl > 1) wnext = mrow[j0 + 1];
;         __syncthreads();
.LBB0_1331:
	s_add_i32 s0, s8, 0x100
	s_ashr_i32 s0, s0, 6
	s_sub_i32 s19, s0, s24
	s_ashr_i32 s25, s24, 31
	v_mad_i64_i32 v[4:5], s[0:1], s24, v186, v[162:163]
	s_lshl_b64 s[0:1], s[24:25], 7
	v_and_b32_e32 v8, 63, v1
	v_lshl_add_u64 v[6:7], v[164:165], 0, s[0:1]
	global_load_dwordx4 v[142:145], v[4:5], off
	global_load_dwordx4 v[146:149], v[6:7], off
	v_lshl_or_b32 v4, s24, 6, v8
	v_ashrrev_i32_e32 v5, 31, v4
	v_lshl_add_u64 v[4:5], v[4:5], 2, s[20:21]
	global_load_dword v151, v[4:5], off
	s_cmp_lt_i32 s19, 2
	s_cbranch_scc1 .Lpd1_one
	s_add_i32 s6, s24, 1
	s_ashr_i32 s7, s6, 31
	v_mad_i64_i32 v[4:5], s[0:1], s6, v186, v[162:163]
	s_lshl_b64 s[0:1], s[6:7], 7
	v_lshl_or_b32 v9, s6, 6, v8
	v_lshl_add_u64 v[6:7], v[164:165], 0, s[0:1]
	global_load_dwordx4 v[66:69], v[4:5], off
	global_load_dwordx4 v[70:73], v[6:7], off
	v_mov_b32_e32 v4, v9
	v_ashrrev_i32_e32 v5, 31, v4
	v_lshl_add_u64 v[4:5], v[4:5], 2, s[20:21]
	global_load_dword v74, v[4:5], off
	v_add3_u32 v2, v171, v182, s41
	s_waitcnt vmcnt(5)
	ds_write_b128 v215, v[142:145]
	s_waitcnt vmcnt(4)
	ds_write2_b64 v2, v[146:147], v[148:149] offset1:1
	s_waitcnt vmcnt(3)
	s_and_saveexec_b64 s[6:7], s[2:3]
	v_add_u32_e32 v2, 0, v172
	ds_write_b32 v2, v151 offset:17920
	s_or_b64 exec, exec, s[6:7]
	v_add_u32_e32 v2, v173, v182
	s_waitcnt vmcnt(2)
	ds_write_b128 v2, v[66:69] offset:18432
	s_waitcnt vmcnt(1)
	ds_write2_b64 v184, v[70:71], v[72:73] offset1:1
	s_waitcnt vmcnt(0)
	s_and_saveexec_b64 s[6:7], s[2:3]
	v_add_u32_e32 v2, 0, v172
	ds_write_b32 v2, v74 offset:36352
	s_or_b64 exec, exec, s[6:7]
	s_branch .LBB0_1341
.Lpd1_one:
	v_add3_u32 v2, v171, v182, s41
	s_waitcnt vmcnt(2)
	ds_write_b128 v215, v[142:145]
	s_waitcnt vmcnt(1)
	ds_write2_b64 v2, v[146:147], v[148:149] offset1:1
	s_waitcnt vmcnt(0)
	s_and_saveexec_b64 s[6:7], s[2:3]
	v_add_u32_e32 v2, 0, v172
	ds_write_b32 v2, v151 offset:17920
	s_or_b64 exec, exec, s[6:7]
